# modulation / shift-bias GEMV loops (P0, P1): next 16-row batch cache lines touched one iteration ahead, counted vmcnt ladder
# speedup vs baseline: 1.0174x; 1.0017x over previous
; __device__ __forceinline__ void p0_mod_item(const float* sc, const float* Wm, const float* bm, float* mod, int j0, float* red, int wid, int lane, int tid) {
;     const int cl = lane & 31, kh = lane >> 5;
;     float acc[4] = {0.f, 0.f, 0.f, 0.f};
; #pragma unroll 16
;     for (int i = 0; i < 64; ++i) {
;         const int k = wid * 128 + 2 * i + kh; const float wv = Wm[(size_t)k * 3072 + j0 + cl];
; #pragma unroll
;         for (int b = 0; b < 4; ++b) acc[b] += sc[b * 1024 + k] * wv;
;     }
.LBB0_22:
	s_cmp_lt_u32 s11, 96
	s_cselect_b32 s98, 0x60000, 0
	s_mov_b32 s99, 0
	v_add_u32_e32 v84, s11, v31
	v_add_u32_e32 v78, 0x1000, v33
	v_add_u32_e32 v80, 0x2000, v33
	v_add_u32_e32 v82, 0x3000, v33
	v_mad_i64_i32 v[34:35], s[14:15], v84, s16, v[6:7]
	ds_read2_b32 v[18:19], v33 offset1:2
	ds_read2_b32 v[16:17], v33 offset0:4 offset1:6
	ds_read2_b32 v[14:15], v33 offset0:8 offset1:10
	ds_read2_b32 v[12:13], v33 offset0:12 offset1:14
	ds_read2_b32 v[20:21], v33 offset0:16 offset1:18
	ds_read2_b32 v[22:23], v33 offset0:20 offset1:22
	ds_read2_b32 v[24:25], v33 offset0:24 offset1:26
	ds_read2_b32 v[26:27], v33 offset0:28 offset1:30
	ds_read2_b32 v[36:37], v78 offset1:2
	ds_read2_b32 v[38:39], v80 offset1:2
	ds_read2_b32 v[40:41], v82 offset1:2
	ds_read2_b32 v[42:43], v78 offset0:4 offset1:6
	ds_read2_b32 v[44:45], v80 offset0:4 offset1:6
	ds_read2_b32 v[46:47], v82 offset0:4 offset1:6
	ds_read2_b32 v[48:49], v78 offset0:8 offset1:10
	ds_read2_b32 v[50:51], v80 offset0:8 offset1:10
	ds_read2_b32 v[52:53], v82 offset0:8 offset1:10
	ds_read2_b32 v[54:55], v78 offset0:12 offset1:14
	ds_read2_b32 v[56:57], v80 offset0:12 offset1:14
	ds_read2_b32 v[58:59], v82 offset0:12 offset1:14
	ds_read2_b32 v[60:61], v78 offset0:16 offset1:18
	ds_read2_b32 v[62:63], v80 offset0:16 offset1:18
	ds_read2_b32 v[64:65], v82 offset0:16 offset1:18
	ds_read2_b32 v[66:67], v78 offset0:20 offset1:22
	ds_read2_b32 v[68:69], v80 offset0:20 offset1:22
	ds_read2_b32 v[70:71], v82 offset0:20 offset1:22
	ds_read2_b32 v[72:73], v78 offset0:24 offset1:26
	ds_read2_b32 v[74:75], v80 offset0:24 offset1:26
	ds_read2_b32 v[76:77], v82 offset0:24 offset1:26
	ds_read2_b32 v[78:79], v78 offset0:28 offset1:30
	ds_read2_b32 v[80:81], v80 offset0:28 offset1:30
	ds_read2_b32 v[82:83], v82 offset0:28 offset1:30
	v_lshl_add_u64 v[186:187], v[34:35], 0, s[98:99]
	global_load_dword v34, v[34:35], off
	v_add_u32_e32 v85, 2, v84
	v_add_u32_e32 v86, 4, v84
	v_add_u32_e32 v88, 6, v84
	v_add_u32_e32 v90, 8, v84
	v_add_u32_e32 v92, 10, v84
	v_add_u32_e32 v94, 12, v84
	v_add_u32_e32 v96, 14, v84
	v_add_u32_e32 v98, 16, v84
	v_add_u32_e32 v100, 18, v84
	v_add_u32_e32 v102, 20, v84
	v_add_u32_e32 v104, 22, v84
	v_add_u32_e32 v106, 24, v84
	v_add_u32_e32 v108, 26, v84
	v_add_u32_e32 v110, 28, v84
	v_add_u32_e32 v112, 30, v84
	v_mad_i64_i32 v[84:85], s[14:15], v85, s16, v[6:7]
	v_mad_i64_i32 v[86:87], s[14:15], v86, s16, v[6:7]
	v_mad_i64_i32 v[88:89], s[14:15], v88, s16, v[6:7]
	v_mad_i64_i32 v[90:91], s[14:15], v90, s16, v[6:7]
	v_mad_i64_i32 v[92:93], s[14:15], v92, s16, v[6:7]
	v_mad_i64_i32 v[94:95], s[14:15], v94, s16, v[6:7]
	v_mad_i64_i32 v[96:97], s[14:15], v96, s16, v[6:7]
	v_mad_i64_i32 v[98:99], s[14:15], v98, s16, v[6:7]
	v_mad_i64_i32 v[100:101], s[14:15], v100, s16, v[6:7]
	v_mad_i64_i32 v[102:103], s[14:15], v102, s16, v[6:7]
	v_mad_i64_i32 v[104:105], s[14:15], v104, s16, v[6:7]
	v_mad_i64_i32 v[106:107], s[14:15], v106, s16, v[6:7]
	v_mad_i64_i32 v[108:109], s[14:15], v108, s16, v[6:7]
	v_mad_i64_i32 v[110:111], s[14:15], v110, s16, v[6:7]
	v_mad_i64_i32 v[112:113], s[14:15], v112, s16, v[6:7]
	v_lshl_add_u64 v[188:189], v[84:85], 0, s[98:99]
	global_load_dword v84, v[84:85], off
	s_nop 0
	v_lshl_add_u64 v[190:191], v[86:87], 0, s[98:99]
	global_load_dword v86, v[86:87], off
	s_nop 0
	v_lshl_add_u64 v[192:193], v[88:89], 0, s[98:99]
	global_load_dword v88, v[88:89], off
	s_nop 0
	v_lshl_add_u64 v[194:195], v[90:91], 0, s[98:99]
	global_load_dword v90, v[90:91], off
	s_nop 0
	v_lshl_add_u64 v[196:197], v[92:93], 0, s[98:99]
	global_load_dword v92, v[92:93], off
	s_nop 0
	v_lshl_add_u64 v[198:199], v[94:95], 0, s[98:99]
	global_load_dword v94, v[94:95], off
	s_nop 0
	v_lshl_add_u64 v[200:201], v[96:97], 0, s[98:99]
	global_load_dword v96, v[96:97], off
	s_nop 0
	v_lshl_add_u64 v[202:203], v[98:99], 0, s[98:99]
	global_load_dword v98, v[98:99], off
	s_nop 0
	v_lshl_add_u64 v[204:205], v[100:101], 0, s[98:99]
	global_load_dword v100, v[100:101], off
	s_nop 0
	v_lshl_add_u64 v[206:207], v[102:103], 0, s[98:99]
	global_load_dword v102, v[102:103], off
	s_nop 0
	v_lshl_add_u64 v[208:209], v[104:105], 0, s[98:99]
	global_load_dword v104, v[104:105], off
	s_nop 0
	v_lshl_add_u64 v[210:211], v[106:107], 0, s[98:99]
	global_load_dword v106, v[106:107], off
	s_nop 0
	v_lshl_add_u64 v[212:213], v[108:109], 0, s[98:99]
	global_load_dword v108, v[108:109], off
	s_nop 0
	v_lshl_add_u64 v[214:215], v[110:111], 0, s[98:99]
	global_load_dword v110, v[110:111], off
	s_nop 0
	v_lshl_add_u64 v[216:217], v[112:113], 0, s[98:99]
	global_load_dword v112, v[112:113], off
	global_load_dword v218, v[186:187], off
	global_load_dword v218, v[188:189], off
	global_load_dword v218, v[190:191], off
	global_load_dword v218, v[192:193], off
	global_load_dword v218, v[194:195], off
	global_load_dword v218, v[196:197], off
	global_load_dword v218, v[198:199], off
	global_load_dword v218, v[200:201], off
	global_load_dword v218, v[202:203], off
	global_load_dword v218, v[204:205], off
	global_load_dword v218, v[206:207], off
	global_load_dword v218, v[208:209], off
	global_load_dword v218, v[210:211], off
	global_load_dword v218, v[212:213], off
	global_load_dword v218, v[214:215], off
	global_load_dword v218, v[216:217], off
	s_waitcnt lgkmcnt(14)
; __device__ __forceinline__ void p0_mod_item(const float* sc, const float* Wm, const float* bm, float* mod, int j0, float* red, int wid, int lane, int tid) {
;     ...
;     for (int i = 0; i < 64; ++i) {
;         const int k = wid * 128 + 2 * i + kh; const float wv = Wm[(size_t)k * 3072 + j0 + cl];
; #pragma unroll
;         for (int b = 0; b < 4; ++b) acc[b] += sc[b * 1024 + k] * wv;
;     }
; #pragma unroll
;     for (int b = 0; b < 4; ++b) acc[b] += __shfl_xor(acc[b], 32);
;     if (lane < 32) {
; #pragma unroll
;         for (int b = 0; b < 4; ++b) red[(wid * 4 + b) * 32 + cl] = acc[b];
;     }
	v_mov_b32_e32 v114, v18
	v_mov_b32_e32 v115, v36
	v_mov_b32_e32 v116, v38
	v_mov_b32_e32 v117, v40
	v_mov_b32_e32 v36, v19
	v_mov_b32_e32 v40, v39
	v_mov_b32_e32 v18, v16
	v_mov_b32_e32 v19, v42
	v_mov_b32_e32 v38, v44
	v_mov_b32_e32 v39, v46
	v_mov_b32_e32 v42, v17
	v_mov_b32_e32 v46, v45
	v_mov_b32_e32 v16, v14
	v_mov_b32_e32 v17, v48
	v_mov_b32_e32 v44, v50
	v_mov_b32_e32 v45, v52
	v_mov_b32_e32 v48, v15
	v_mov_b32_e32 v52, v51
	v_mov_b32_e32 v14, v12
	v_mov_b32_e32 v15, v54
	s_waitcnt lgkmcnt(13)
	v_mov_b32_e32 v50, v56
	s_waitcnt lgkmcnt(12)
	v_mov_b32_e32 v51, v58
	v_mov_b32_e32 v54, v13
	v_mov_b32_e32 v58, v57
	v_mov_b32_e32 v12, v20
	s_waitcnt lgkmcnt(11)
	v_mov_b32_e32 v13, v60
	s_waitcnt lgkmcnt(10)
	v_mov_b32_e32 v56, v62
	s_waitcnt lgkmcnt(9)
	v_mov_b32_e32 v57, v64
	v_mov_b32_e32 v60, v21
	v_mov_b32_e32 v64, v63
	v_mov_b32_e32 v20, v22
	s_waitcnt lgkmcnt(8)
	v_mov_b32_e32 v21, v66
	s_waitcnt lgkmcnt(7)
	v_mov_b32_e32 v62, v68
	s_waitcnt vmcnt(31)
	v_pk_fma_f32 v[8:9], v[34:35], v[114:115], v[8:9] op_sel_hi:[0,1,1]
	v_pk_fma_f32 v[10:11], v[34:35], v[116:117], v[10:11] op_sel_hi:[0,1,1]
	s_waitcnt lgkmcnt(6)
	v_mov_b32_e32 v63, v70
	v_mov_b32_e32 v66, v23
	v_mov_b32_e32 v70, v69
	v_mov_b32_e32 v22, v24
	s_waitcnt lgkmcnt(5)
	v_mov_b32_e32 v23, v72
	s_waitcnt lgkmcnt(4)
	v_mov_b32_e32 v68, v74
	s_waitcnt lgkmcnt(3)
	v_mov_b32_e32 v69, v76
	v_mov_b32_e32 v72, v25
	v_mov_b32_e32 v76, v75
	v_mov_b32_e32 v24, v26
	s_waitcnt lgkmcnt(2)
	v_mov_b32_e32 v25, v78
	v_mov_b32_e32 v78, v27
	s_waitcnt lgkmcnt(1)
	v_mov_b32_e32 v26, v80
	s_waitcnt lgkmcnt(0)
	v_mov_b32_e32 v27, v82
	s_add_i32 s11, s11, 32
	v_mov_b32_e32 v82, v81
	v_add_u32_e32 v33, 0x80, v33
	s_cmpk_eq_i32 s11, 0x80
	s_waitcnt vmcnt(30)
	v_pk_fma_f32 v[8:9], v[84:85], v[36:37], v[8:9] op_sel_hi:[0,1,1]
	v_pk_fma_f32 v[10:11], v[84:85], v[40:41], v[10:11] op_sel_hi:[0,1,1]
	s_waitcnt vmcnt(29)
	v_pk_fma_f32 v[8:9], v[86:87], v[18:19], v[8:9] op_sel_hi:[0,1,1]
	v_pk_fma_f32 v[10:11], v[86:87], v[38:39], v[10:11] op_sel_hi:[0,1,1]
	s_waitcnt vmcnt(28)
	v_pk_fma_f32 v[8:9], v[88:89], v[42:43], v[8:9] op_sel_hi:[0,1,1]
	v_pk_fma_f32 v[10:11], v[88:89], v[46:47], v[10:11] op_sel_hi:[0,1,1]
	s_waitcnt vmcnt(27)
	v_pk_fma_f32 v[8:9], v[90:91], v[16:17], v[8:9] op_sel_hi:[0,1,1]
	v_pk_fma_f32 v[10:11], v[90:91], v[44:45], v[10:11] op_sel_hi:[0,1,1]
	s_waitcnt vmcnt(26)
	v_pk_fma_f32 v[8:9], v[92:93], v[48:49], v[8:9] op_sel_hi:[0,1,1]
	v_pk_fma_f32 v[10:11], v[92:93], v[52:53], v[10:11] op_sel_hi:[0,1,1]
	s_waitcnt vmcnt(25)
	v_pk_fma_f32 v[8:9], v[94:95], v[14:15], v[8:9] op_sel_hi:[0,1,1]
	v_pk_fma_f32 v[10:11], v[94:95], v[50:51], v[10:11] op_sel_hi:[0,1,1]
	s_waitcnt vmcnt(24)
	v_pk_fma_f32 v[8:9], v[96:97], v[54:55], v[8:9] op_sel_hi:[0,1,1]
	v_pk_fma_f32 v[10:11], v[96:97], v[58:59], v[10:11] op_sel_hi:[0,1,1]
	s_waitcnt vmcnt(23)
	v_pk_fma_f32 v[8:9], v[98:99], v[12:13], v[8:9] op_sel_hi:[0,1,1]
	v_pk_fma_f32 v[10:11], v[98:99], v[56:57], v[10:11] op_sel_hi:[0,1,1]
	s_waitcnt vmcnt(22)
	v_pk_fma_f32 v[8:9], v[100:101], v[60:61], v[8:9] op_sel_hi:[0,1,1]
	v_pk_fma_f32 v[10:11], v[100:101], v[64:65], v[10:11] op_sel_hi:[0,1,1]
	s_waitcnt vmcnt(21)
	v_pk_fma_f32 v[8:9], v[102:103], v[20:21], v[8:9] op_sel_hi:[0,1,1]
	v_pk_fma_f32 v[10:11], v[102:103], v[62:63], v[10:11] op_sel_hi:[0,1,1]
	s_waitcnt vmcnt(20)
	v_pk_fma_f32 v[8:9], v[104:105], v[66:67], v[8:9] op_sel_hi:[0,1,1]
	v_pk_fma_f32 v[10:11], v[104:105], v[70:71], v[10:11] op_sel_hi:[0,1,1]
	s_waitcnt vmcnt(19)
	v_pk_fma_f32 v[8:9], v[106:107], v[22:23], v[8:9] op_sel_hi:[0,1,1]
	v_pk_fma_f32 v[10:11], v[106:107], v[68:69], v[10:11] op_sel_hi:[0,1,1]
	s_waitcnt vmcnt(18)
	v_pk_fma_f32 v[8:9], v[108:109], v[72:73], v[8:9] op_sel_hi:[0,1,1]
	v_pk_fma_f32 v[10:11], v[108:109], v[76:77], v[10:11] op_sel_hi:[0,1,1]
	s_waitcnt vmcnt(17)
	v_pk_fma_f32 v[8:9], v[110:111], v[24:25], v[8:9] op_sel_hi:[0,1,1]
	v_pk_fma_f32 v[10:11], v[110:111], v[26:27], v[10:11] op_sel_hi:[0,1,1]
	s_waitcnt vmcnt(16)
	v_pk_fma_f32 v[8:9], v[112:113], v[78:79], v[8:9] op_sel_hi:[0,1,1]
	v_pk_fma_f32 v[10:11], v[112:113], v[82:83], v[10:11] op_sel_hi:[0,1,1]
	s_cbranch_scc0 .LBB0_22
	ds_bpermute_b32 v6, v1, v8
	ds_bpermute_b32 v7, v1, v9
	ds_bpermute_b32 v12, v1, v10
	ds_bpermute_b32 v13, v1, v11
	s_and_saveexec_b64 s[14:15], vcc
	s_cbranch_execz .LBB0_25
	s_waitcnt lgkmcnt(2)
	v_add_f32_e32 v7, v9, v7
	v_add_f32_e32 v6, v8, v6
	s_waitcnt lgkmcnt(0)
	v_add_f32_e32 v11, v11, v13
	v_add_f32_e32 v10, v10, v12
	ds_write2_b32 v3, v6, v7 offset1:32
	ds_write2_b32 v3, v10, v11 offset0:64 offset1:96

; __device__ __forceinline__ void p1_bias_item(const float* sc, const float* W, float* bias, int j0, float* red, int wid, int lane, int tid) {
;     const int cl = lane & 31, kh = lane >> 5;
;     float acc[4] = {0.f, 0.f, 0.f, 0.f};
; #pragma unroll 16
;     for (int i = 0; i < 64; ++i) {
;         const int k = wid * 128 + 2 * i + kh; const float wv = W[(size_t)k * OIN + j0 + cl];
; #pragma unroll
;         for (int b = 0; b < 4; ++b) acc[b] += sc[b * 1024 + k] * wv;
;     }
.LBB0_128:
	s_cmp_lt_u32 s6, 96
	s_cselect_b32 s98, 0x80000, 0
	s_mov_b32 s99, 0
	v_add_u32_e32 v18, s6, v28
	v_ashrrev_i32_e32 v19, 31, v18
	v_add_u32_e32 v42, 2, v18
	v_add_u32_e32 v44, 4, v18
	v_add_u32_e32 v52, 6, v18
	v_add_u32_e32 v54, 8, v18
	v_add_u32_e32 v62, 10, v18
	v_add_u32_e32 v64, 12, v18
	v_add_u32_e32 v72, 14, v18
	v_add_u32_e32 v74, 16, v18
	v_add_u32_e32 v82, 18, v18
	v_add_u32_e32 v84, 20, v18
	v_add_u32_e32 v92, 22, v18
	v_add_u32_e32 v94, 24, v18
	v_add_u32_e32 v102, 26, v18
	v_add_u32_e32 v104, 28, v18
	v_add_u32_e32 v112, 30, v18
	v_lshlrev_b64 v[18:19], 14, v[18:19]
	v_add_u32_e32 v43, 0x1000, v31
	v_lshl_add_u64 v[18:19], v[4:5], 0, v[18:19]
	ds_read2_b32 v[16:17], v31 offset1:2
	ds_read2_b32 v[14:15], v31 offset0:4 offset1:6
	ds_read2_b32 v[12:13], v31 offset0:8 offset1:10
	ds_read2_b32 v[10:11], v31 offset0:12 offset1:14
	v_add_u32_e32 v45, 0x2000, v31
	v_add_u32_e32 v53, 0x3000, v31
	ds_read2_b32 v[20:21], v31 offset0:16 offset1:18
	ds_read2_b32 v[22:23], v31 offset0:20 offset1:22
	ds_read2_b32 v[32:33], v31 offset0:24 offset1:26
	ds_read2_b32 v[34:35], v31 offset0:28 offset1:30
	ds_read2_b32 v[36:37], v43 offset1:2
	ds_read2_b32 v[38:39], v45 offset1:2
	ds_read2_b32 v[40:41], v53 offset1:2
	ds_read2_b32 v[46:47], v43 offset0:4 offset1:6
	ds_read2_b32 v[48:49], v45 offset0:4 offset1:6
	ds_read2_b32 v[50:51], v53 offset0:4 offset1:6
	ds_read2_b32 v[56:57], v43 offset0:8 offset1:10
	ds_read2_b32 v[58:59], v45 offset0:8 offset1:10
	ds_read2_b32 v[60:61], v53 offset0:8 offset1:10
	ds_read2_b32 v[66:67], v43 offset0:12 offset1:14
	ds_read2_b32 v[68:69], v45 offset0:12 offset1:14
	ds_read2_b32 v[70:71], v53 offset0:12 offset1:14
	ds_read2_b32 v[76:77], v43 offset0:16 offset1:18
	ds_read2_b32 v[78:79], v45 offset0:16 offset1:18
	ds_read2_b32 v[80:81], v53 offset0:16 offset1:18
	ds_read2_b32 v[86:87], v43 offset0:20 offset1:22
	ds_read2_b32 v[88:89], v45 offset0:20 offset1:22
	ds_read2_b32 v[90:91], v53 offset0:20 offset1:22
	ds_read2_b32 v[96:97], v43 offset0:24 offset1:26
	ds_read2_b32 v[98:99], v45 offset0:24 offset1:26
	ds_read2_b32 v[100:101], v53 offset0:24 offset1:26
	ds_read2_b32 v[106:107], v43 offset0:28 offset1:30
	ds_read2_b32 v[108:109], v45 offset0:28 offset1:30
	ds_read2_b32 v[110:111], v53 offset0:28 offset1:30
	v_lshl_add_u64 v[186:187], v[18:19], 0, s[98:99]
	global_load_dword v18, v[18:19], off
	v_ashrrev_i32_e32 v43, 31, v42
	v_ashrrev_i32_e32 v45, 31, v44
	v_ashrrev_i32_e32 v53, 31, v52
	v_ashrrev_i32_e32 v55, 31, v54
	v_ashrrev_i32_e32 v63, 31, v62
	v_ashrrev_i32_e32 v65, 31, v64
	v_ashrrev_i32_e32 v73, 31, v72
	v_ashrrev_i32_e32 v75, 31, v74
	v_ashrrev_i32_e32 v83, 31, v82
	v_ashrrev_i32_e32 v85, 31, v84
	v_ashrrev_i32_e32 v93, 31, v92
	v_ashrrev_i32_e32 v95, 31, v94
	v_ashrrev_i32_e32 v103, 31, v102
	v_ashrrev_i32_e32 v105, 31, v104
	v_ashrrev_i32_e32 v113, 31, v112
	v_lshlrev_b64 v[42:43], 14, v[42:43]
	v_lshlrev_b64 v[44:45], 14, v[44:45]
	v_lshlrev_b64 v[52:53], 14, v[52:53]
	v_lshlrev_b64 v[54:55], 14, v[54:55]
	v_lshlrev_b64 v[62:63], 14, v[62:63]
	v_lshlrev_b64 v[64:65], 14, v[64:65]
	v_lshlrev_b64 v[72:73], 14, v[72:73]
	v_lshlrev_b64 v[74:75], 14, v[74:75]
	v_lshlrev_b64 v[82:83], 14, v[82:83]
	v_lshlrev_b64 v[84:85], 14, v[84:85]
	v_lshlrev_b64 v[92:93], 14, v[92:93]
	v_lshlrev_b64 v[94:95], 14, v[94:95]
	v_lshlrev_b64 v[102:103], 14, v[102:103]
	v_lshlrev_b64 v[104:105], 14, v[104:105]
	v_lshlrev_b64 v[112:113], 14, v[112:113]
	v_lshl_add_u64 v[42:43], v[4:5], 0, v[42:43]
	v_lshl_add_u64 v[44:45], v[4:5], 0, v[44:45]
	v_lshl_add_u64 v[52:53], v[4:5], 0, v[52:53]
	v_lshl_add_u64 v[54:55], v[4:5], 0, v[54:55]
	v_lshl_add_u64 v[62:63], v[4:5], 0, v[62:63]
	v_lshl_add_u64 v[64:65], v[4:5], 0, v[64:65]
	v_lshl_add_u64 v[72:73], v[4:5], 0, v[72:73]
	v_lshl_add_u64 v[74:75], v[4:5], 0, v[74:75]
	v_lshl_add_u64 v[82:83], v[4:5], 0, v[82:83]
	v_lshl_add_u64 v[84:85], v[4:5], 0, v[84:85]
	v_lshl_add_u64 v[92:93], v[4:5], 0, v[92:93]
	v_lshl_add_u64 v[94:95], v[4:5], 0, v[94:95]
	v_lshl_add_u64 v[102:103], v[4:5], 0, v[102:103]
	v_lshl_add_u64 v[104:105], v[4:5], 0, v[104:105]
	v_lshl_add_u64 v[112:113], v[4:5], 0, v[112:113]
	v_lshl_add_u64 v[188:189], v[42:43], 0, s[98:99]
	global_load_dword v42, v[42:43], off
	s_nop 0
	v_lshl_add_u64 v[190:191], v[44:45], 0, s[98:99]
	global_load_dword v44, v[44:45], off
	s_nop 0
	v_lshl_add_u64 v[192:193], v[52:53], 0, s[98:99]
	global_load_dword v52, v[52:53], off
	s_nop 0
	v_lshl_add_u64 v[194:195], v[54:55], 0, s[98:99]
	global_load_dword v54, v[54:55], off
	s_nop 0
	v_lshl_add_u64 v[196:197], v[62:63], 0, s[98:99]
	global_load_dword v62, v[62:63], off
	s_nop 0
	v_lshl_add_u64 v[198:199], v[64:65], 0, s[98:99]
	global_load_dword v64, v[64:65], off
	s_nop 0
	v_lshl_add_u64 v[200:201], v[72:73], 0, s[98:99]
	global_load_dword v72, v[72:73], off
	s_nop 0
	v_lshl_add_u64 v[202:203], v[74:75], 0, s[98:99]
	global_load_dword v74, v[74:75], off
	s_nop 0
	v_lshl_add_u64 v[204:205], v[82:83], 0, s[98:99]
	global_load_dword v82, v[82:83], off
	s_nop 0
	v_lshl_add_u64 v[206:207], v[84:85], 0, s[98:99]
	global_load_dword v84, v[84:85], off
	s_nop 0
	v_lshl_add_u64 v[208:209], v[92:93], 0, s[98:99]
	global_load_dword v92, v[92:93], off
	s_nop 0
	v_lshl_add_u64 v[210:211], v[94:95], 0, s[98:99]
	global_load_dword v94, v[94:95], off
	s_nop 0
	v_lshl_add_u64 v[212:213], v[102:103], 0, s[98:99]
	global_load_dword v102, v[102:103], off
	s_nop 0
	v_lshl_add_u64 v[214:215], v[104:105], 0, s[98:99]
	global_load_dword v104, v[104:105], off
	s_nop 0
	v_lshl_add_u64 v[216:217], v[112:113], 0, s[98:99]
	global_load_dword v112, v[112:113], off
	global_load_dword v218, v[186:187], off
	global_load_dword v218, v[188:189], off
	global_load_dword v218, v[190:191], off
	global_load_dword v218, v[192:193], off
	global_load_dword v218, v[194:195], off
	global_load_dword v218, v[196:197], off
	global_load_dword v218, v[198:199], off
	global_load_dword v218, v[200:201], off
	global_load_dword v218, v[202:203], off
	global_load_dword v218, v[204:205], off
	global_load_dword v218, v[206:207], off
	global_load_dword v218, v[208:209], off
	global_load_dword v218, v[210:211], off
	global_load_dword v218, v[212:213], off
	global_load_dword v218, v[214:215], off
	global_load_dword v218, v[216:217], off
	s_waitcnt lgkmcnt(14)
; __device__ __forceinline__ void p1_bias_item(const float* sc, const float* W, float* bias, int j0, float* red, int wid, int lane, int tid) {
;     ...
;     for (int i = 0; i < 64; ++i) {
;         const int k = wid * 128 + 2 * i + kh; const float wv = W[(size_t)k * OIN + j0 + cl];
; #pragma unroll
;         for (int b = 0; b < 4; ++b) acc[b] += sc[b * 1024 + k] * wv;
;     }
; #pragma unroll
;     for (int b = 0; b < 4; ++b) acc[b] += __shfl_xor(acc[b], 32);
;     if (lane < 32) {
; #pragma unroll
;         for (int b = 0; b < 4; ++b) red[(wid * 4 + b) * 32 + cl] = acc[b];
;     }
	v_mov_b32_e32 v114, v16
	v_mov_b32_e32 v115, v36
	v_mov_b32_e32 v116, v38
	v_mov_b32_e32 v117, v40
	v_mov_b32_e32 v36, v17
	v_mov_b32_e32 v40, v39
	v_mov_b32_e32 v16, v14
	v_mov_b32_e32 v17, v46
	v_mov_b32_e32 v38, v48
	v_mov_b32_e32 v39, v50
	v_mov_b32_e32 v46, v15
	v_mov_b32_e32 v50, v49
	v_mov_b32_e32 v14, v12
	v_mov_b32_e32 v15, v56
	v_mov_b32_e32 v48, v58
	v_mov_b32_e32 v49, v60
	v_mov_b32_e32 v56, v13
	v_mov_b32_e32 v60, v59
	v_mov_b32_e32 v12, v10
	v_mov_b32_e32 v13, v66
	s_waitcnt lgkmcnt(13)
	v_mov_b32_e32 v58, v68
	s_waitcnt lgkmcnt(12)
	v_mov_b32_e32 v59, v70
	v_mov_b32_e32 v66, v11
	v_mov_b32_e32 v70, v69
	v_mov_b32_e32 v10, v20
	s_waitcnt lgkmcnt(11)
	v_mov_b32_e32 v11, v76
	s_waitcnt lgkmcnt(10)
	v_mov_b32_e32 v68, v78
	s_waitcnt lgkmcnt(9)
	v_mov_b32_e32 v69, v80
	v_mov_b32_e32 v76, v21
	v_mov_b32_e32 v80, v79
	v_mov_b32_e32 v20, v22
	s_waitcnt lgkmcnt(8)
	v_mov_b32_e32 v21, v86
	s_waitcnt lgkmcnt(7)
	v_mov_b32_e32 v78, v88
	s_waitcnt vmcnt(31)
	v_pk_fma_f32 v[6:7], v[18:19], v[114:115], v[6:7] op_sel_hi:[0,1,1]
	v_pk_fma_f32 v[8:9], v[18:19], v[116:117], v[8:9] op_sel_hi:[0,1,1]
	s_waitcnt lgkmcnt(6)
	v_mov_b32_e32 v79, v90
	v_mov_b32_e32 v86, v23
	v_mov_b32_e32 v90, v89
	v_mov_b32_e32 v22, v32
	s_waitcnt lgkmcnt(5)
	v_mov_b32_e32 v23, v96
	s_waitcnt lgkmcnt(4)
	v_mov_b32_e32 v88, v98
	s_waitcnt lgkmcnt(3)
	v_mov_b32_e32 v89, v100
	v_mov_b32_e32 v96, v33
	v_mov_b32_e32 v100, v99
	v_mov_b32_e32 v32, v34
	s_waitcnt lgkmcnt(2)
	v_mov_b32_e32 v33, v106
	s_waitcnt lgkmcnt(1)
	v_mov_b32_e32 v98, v108
	s_waitcnt lgkmcnt(0)
	v_mov_b32_e32 v99, v110
	s_add_i32 s6, s6, 32
	v_mov_b32_e32 v106, v35
	v_mov_b32_e32 v110, v109
	v_add_u32_e32 v31, 0x80, v31
	s_cmpk_eq_i32 s6, 0x80
	s_waitcnt vmcnt(30)
	v_pk_fma_f32 v[6:7], v[42:43], v[36:37], v[6:7] op_sel_hi:[0,1,1]
	v_pk_fma_f32 v[8:9], v[42:43], v[40:41], v[8:9] op_sel_hi:[0,1,1]
	s_waitcnt vmcnt(29)
	v_pk_fma_f32 v[6:7], v[44:45], v[16:17], v[6:7] op_sel_hi:[0,1,1]
	v_pk_fma_f32 v[8:9], v[44:45], v[38:39], v[8:9] op_sel_hi:[0,1,1]
	s_waitcnt vmcnt(28)
	v_pk_fma_f32 v[6:7], v[52:53], v[46:47], v[6:7] op_sel_hi:[0,1,1]
	v_pk_fma_f32 v[8:9], v[52:53], v[50:51], v[8:9] op_sel_hi:[0,1,1]
	s_waitcnt vmcnt(27)
	v_pk_fma_f32 v[6:7], v[54:55], v[14:15], v[6:7] op_sel_hi:[0,1,1]
	v_pk_fma_f32 v[8:9], v[54:55], v[48:49], v[8:9] op_sel_hi:[0,1,1]
	s_waitcnt vmcnt(26)
	v_pk_fma_f32 v[6:7], v[62:63], v[56:57], v[6:7] op_sel_hi:[0,1,1]
	v_pk_fma_f32 v[8:9], v[62:63], v[60:61], v[8:9] op_sel_hi:[0,1,1]
	s_waitcnt vmcnt(25)
	v_pk_fma_f32 v[6:7], v[64:65], v[12:13], v[6:7] op_sel_hi:[0,1,1]
	v_pk_fma_f32 v[8:9], v[64:65], v[58:59], v[8:9] op_sel_hi:[0,1,1]
	s_waitcnt vmcnt(24)
	v_pk_fma_f32 v[6:7], v[72:73], v[66:67], v[6:7] op_sel_hi:[0,1,1]
	v_pk_fma_f32 v[8:9], v[72:73], v[70:71], v[8:9] op_sel_hi:[0,1,1]
	s_waitcnt vmcnt(23)
	v_pk_fma_f32 v[6:7], v[74:75], v[10:11], v[6:7] op_sel_hi:[0,1,1]
	v_pk_fma_f32 v[8:9], v[74:75], v[68:69], v[8:9] op_sel_hi:[0,1,1]
	s_waitcnt vmcnt(22)
	v_pk_fma_f32 v[6:7], v[82:83], v[76:77], v[6:7] op_sel_hi:[0,1,1]
	v_pk_fma_f32 v[8:9], v[82:83], v[80:81], v[8:9] op_sel_hi:[0,1,1]
	s_waitcnt vmcnt(21)
	v_pk_fma_f32 v[6:7], v[84:85], v[20:21], v[6:7] op_sel_hi:[0,1,1]
	v_pk_fma_f32 v[8:9], v[84:85], v[78:79], v[8:9] op_sel_hi:[0,1,1]
	s_waitcnt vmcnt(20)
	v_pk_fma_f32 v[6:7], v[92:93], v[86:87], v[6:7] op_sel_hi:[0,1,1]
	v_pk_fma_f32 v[8:9], v[92:93], v[90:91], v[8:9] op_sel_hi:[0,1,1]
	s_waitcnt vmcnt(19)
	v_pk_fma_f32 v[6:7], v[94:95], v[22:23], v[6:7] op_sel_hi:[0,1,1]
	v_pk_fma_f32 v[8:9], v[94:95], v[88:89], v[8:9] op_sel_hi:[0,1,1]
	s_waitcnt vmcnt(18)
	v_pk_fma_f32 v[6:7], v[102:103], v[96:97], v[6:7] op_sel_hi:[0,1,1]
	v_pk_fma_f32 v[8:9], v[102:103], v[100:101], v[8:9] op_sel_hi:[0,1,1]
	s_waitcnt vmcnt(17)
	v_pk_fma_f32 v[6:7], v[104:105], v[32:33], v[6:7] op_sel_hi:[0,1,1]
	v_pk_fma_f32 v[8:9], v[104:105], v[98:99], v[8:9] op_sel_hi:[0,1,1]
	s_waitcnt vmcnt(16)
	v_pk_fma_f32 v[6:7], v[112:113], v[106:107], v[6:7] op_sel_hi:[0,1,1]
	v_pk_fma_f32 v[8:9], v[112:113], v[110:111], v[8:9] op_sel_hi:[0,1,1]
	s_cbranch_scc0 .LBB0_128
	ds_bpermute_b32 v4, v26, v6
	ds_bpermute_b32 v5, v26, v7
	ds_bpermute_b32 v10, v26, v8
	ds_bpermute_b32 v11, v26, v9
	s_and_saveexec_b64 s[6:7], vcc
	s_cbranch_execz .LBB0_131
	s_waitcnt lgkmcnt(2)
	v_add_f32_e32 v5, v7, v5
	v_add_f32_e32 v4, v6, v4
	s_waitcnt lgkmcnt(0)
	v_add_f32_e32 v9, v9, v11
	v_add_f32_e32 v8, v8, v10
	ds_write2_b32 v25, v4, v5 offset1:32
	ds_write2_b32 v25, v8, v9 offset0:64 offset1:96
